# combo18 + o-norm pass issues all eight row loads before its first wait + rmsnorm w_extra slab loads issued together
# baseline (speedup 1.0000x reference)
; template <bool EXTRA>
; __device__ __forceinline__ void rmsnorm_rows(const float* __restrict__ x0, const float* __restrict__ x1, const float* __restrict__ g,
;                                              const float* __restrict__ wex, bf16_t* __restrict__ xn, float* __restrict__ ba, LAS f32x4* slab) {
;     const int lane = threadIdx.x & 63, wid = threadIdx.x >> 6;
;     const int gw = blockIdx.x * 8 + wid, nw = gridDim.x * 8;
;     float4 gg[4];
; #pragma unroll
;     for (int i = 0; i < 4; ++i) gg[i] = *(const float4*)(g + lane * 4 + 256 * i);
;     if constexpr (EXTRA) {
;         for (int idx = threadIdx.x; idx < 2048; idx += 512) { const int k = idx >> 1, half = idx & 1, ln = (k & 255) >> 2, i = k >> 8, e = k & 3;
;             slab[((i * 4 + e) * 2 + half) * 64 + ln] = *(const f32x4*)(wex + (size_t)k * LDWIN + half * 4); }
;         __syncthreads();
;     }
;     float4 vn_[4];
;     if (gw < MTOK) { const float* x = gw < MP ? x0 + (size_t)gw * DM : x1 + (size_t)(gw - MP) * DM;
; #pragma unroll
;         for (int i = 0; i < 4; ++i) vn_[i] = *(const float4*)(x + lane * 4 + 256 * i); }
;     for (int row = gw; row < MTOK; row += nw) {
;         float4 v[4]; float ss = 0.f;
; #pragma unroll
;         for (int i = 0; i < 4; ++i) v[i] = vn_[i];
;         { const int rn = (row + nw < MTOK) ? row + nw : row;
;           const float* xn_ = rn < MP ? x0 + (size_t)rn * DM : x1 + (size_t)(rn - MP) * DM;
; #pragma unroll
;           for (int i = 0; i < 4; ++i) vn_[i] = *(const float4*)(xn_ + lane * 4 + 256 * i); }
; #pragma unroll
;         for (int i = 0; i < 4; ++i) ss += v[i].x * v[i].x + v[i].y * v[i].y + v[i].z * v[i].z + v[i].w * v[i].w;
;         ss = wave_sum(ss);
;         const float r = rsqrtf(ss * (1.0f / 1024.0f) + 1e-6f);
;         float a[8] = {0.f, 0.f, 0.f, 0.f, 0.f, 0.f, 0.f, 0.f};
; #pragma unroll
;         for (int i = 0; i < 4; ++i) {
;             float y[4] = {v[i].x * r * gg[i].x, v[i].y * r * gg[i].y, v[i].z * r * gg[i].z, v[i].w * r * gg[i].w};
;             u32x2 w; w.x = cvt_pk_bf16(y[0], y[1]); w.y = cvt_pk_bf16(y[2], y[3]);
;             *(u32x2*)(xn + (size_t)row * DM + lane * 4 + 256 * i) = w;
;             if constexpr (EXTRA) {
; #pragma unroll
;                 for (int e = 0; e < 4; ++e) { const f32x4 w0 = slab[((i * 4 + e) * 2) * 64 + lane], w1 = slab[((i * 4 + e) * 2 + 1) * 64 + lane];
.LBB0_50:
	s_or_b64 exec, exec, s[0:1]
	v_and_b32_e32 v48, 63, v184
	v_lshlrev_b32_e32 v12, 4, v48
	global_load_dwordx4 v[0:3], v12, s[66:67]
	global_load_dwordx4 v[4:7], v12, s[66:67] offset:1024
	global_load_dwordx4 v[8:11], v12, s[66:67] offset:2048
	s_nop 0
	global_load_dwordx4 v[12:15], v12, s[66:67] offset:3072
	v_lshrrev_b32_e32 v18, 1, v184
	s_movk_i32 s0, 0x3420
	v_and_b32_e32 v22, 1, v184
	v_lshlrev_b32_e32 v20, 7, v18
	v_mad_u64_u32 v[18:19], s[0:1], v18, s0, 0
	v_lshl_or_b32 v18, v22, 4, v18
	v_and_b32_e32 v21, 63, v17
	v_lshl_add_u64 v[18:19], s[68:69], 0, v[18:19]
	s_mov_b64 s[0:1], 0x3400
	v_lshlrev_b32_e32 v16, 2, v48
	v_lshlrev_b32_e32 v17, 10, v22
	v_lshl_add_u64 v[18:19], v[18:19], 0, s[0:1]
	s_mov_b64 s[0:1], 0
	v_lshlrev_b32_e32 v21, 4, v21
	s_mov_b64 s[2:3], 0x342000
	s_movk_i32 s4, 0x5ff
	v_mov_b32_e32 v22, v184
	global_load_dwordx4 v[24:27], v[18:19], off
	v_lshl_add_u64 v[18:19], v[18:19], 0, s[2:3]
	global_load_dwordx4 v[202:205], v[18:19], off
	v_lshl_add_u64 v[18:19], v[18:19], 0, s[2:3]
	global_load_dwordx4 v[206:209], v[18:19], off
	v_lshl_add_u64 v[18:19], v[18:19], 0, s[2:3]
	global_load_dwordx4 v[210:213], v[18:19], off
	v_and_b32_e32 v23, 0x180, v20
	v_lshlrev_b32_e32 v23, 4, v23
	v_add3_u32 v23, v23, v17, v21
	s_waitcnt vmcnt(0)
	ds_write_b128 v23, v[24:27] offset:32768
	ds_write_b128 v23, v[202:205] offset:40960
	ds_write_b128 v23, v[206:209] offset:49152
	ds_write_b128 v23, v[210:213] offset:57344
	s_or_b64 exec, exec, s[0:1]
	v_lshrrev_b32_e32 v17, 6, v184
	v_lshl_add_u32 v176, s33, 3, v17
	s_movk_i32 s18, 0x4200
	v_cmp_gt_i32_e32 vcc, s18, v176
	s_waitcnt lgkmcnt(0)
	s_barrier
	s_and_saveexec_b64 s[8:9], vcc
	s_cbranch_execz .LBB0_57
	s_movk_i32 s19, 0x4000
	v_add_u32_e32 v17, 0xffffc000, v176
	v_cmp_gt_i32_e32 vcc, s19, v176
	v_ashrrev_i32_e32 v177, 31, v176
	v_mov_b32_e32 v20, s53
	v_cndmask_b32_e32 v18, v17, v176, vcc
	v_mov_b32_e32 v17, s55
	v_cndmask_b32_e32 v19, 0, v177, vcc
	v_cndmask_b32_e32 v21, v17, v20, vcc
	v_mov_b32_e32 v17, s54
	v_mov_b32_e32 v20, s52
	v_cndmask_b32_e32 v20, v17, v20, vcc
	v_lshlrev_b64 v[18:19], 12, v[18:19]
	v_mov_b32_e32 v179, 0
	v_lshl_add_u64 v[18:19], v[20:21], 0, v[18:19]
	v_lshlrev_b32_e32 v178, 2, v16
	v_lshl_add_u64 v[16:17], v[18:19], 0, v[178:179]
	global_load_dwordx4 v[156:159], v[16:17], off
	global_load_dwordx4 v[148:151], v[16:17], off offset:1024
	global_load_dwordx4 v[152:155], v[16:17], off offset:2048
	global_load_dwordx4 v[108:111], v[16:17], off offset:3072
	v_mbcnt_lo_u32_b32 v16, -1, 0
	v_mbcnt_hi_u32_b32 v16, -1, v16
	v_and_b32_e32 v18, 64, v16
	v_xor_b32_e32 v17, 16, v16
	v_add_u32_e32 v18, 64, v18
	v_cmp_lt_i32_e32 vcc, v17, v18
	v_lshl_add_u32 v144, v48, 4, 0
	v_lshlrev_b64 v[182:183], 11, v[176:177]
	v_cndmask_b32_e32 v17, v16, v17, vcc
	v_lshlrev_b32_e32 v185, 2, v17
	v_xor_b32_e32 v17, 32, v16
	v_cmp_lt_i32_e32 vcc, v17, v18
	v_cmp_eq_u32_e64 s[2:3], 0, v48
	v_lshl_or_b32 v182, v48, 3, v182
	v_cndmask_b32_e32 v16, v16, v17, vcc
	v_lshlrev_b32_e32 v186, 2, v16
	ds_read_b128 v[16:19], v144 offset:32768
	ds_read_b128 v[20:23], v144 offset:33792
	ds_read_b128 v[24:27], v144 offset:34816
	ds_read_b128 v[28:31], v144 offset:35840
	ds_read_b128 v[32:35], v144 offset:36864
	ds_read_b128 v[36:39], v144 offset:37888
	ds_read_b128 v[40:43], v144 offset:38912
	ds_read_b128 v[44:47], v144 offset:39936
	ds_read_b128 v[48:51], v144 offset:40960
	ds_read_b128 v[52:55], v144 offset:41984
	ds_read_b128 v[56:59], v144 offset:43008
	ds_read_b128 v[60:63], v144 offset:44032
	ds_read_b128 v[64:67], v144 offset:45056
	ds_read_b128 v[68:71], v144 offset:46080
	ds_read_b128 v[72:75], v144 offset:47104
	ds_read_b128 v[76:79], v144 offset:48128
	ds_read_b128 v[80:83], v144 offset:49152
	ds_read_b128 v[84:87], v144 offset:50176
	ds_read_b128 v[88:91], v144 offset:51200
	ds_read_b128 v[92:95], v144 offset:52224
	ds_read_b128 v[96:99], v144 offset:53248
	ds_read_b128 v[100:103], v144 offset:54272
	ds_read_b128 v[104:107], v144 offset:55296
	ds_read_b128 v[112:115], v144 offset:56320
	ds_read_b128 v[116:119], v144 offset:57344
	ds_read_b128 v[120:123], v144 offset:58368
	ds_read_b128 v[124:127], v144 offset:59392
	ds_read_b128 v[128:131], v144 offset:60416
	ds_read_b128 v[132:135], v144 offset:61440
	ds_read_b128 v[136:139], v144 offset:62464
	ds_read_b128 v[140:143], v144 offset:63488
	ds_read_b128 v[144:147], v144 offset:64512
	s_lshl_b32 s10, s86, 3
	s_ashr_i32 s11, s10, 31
	v_lshlrev_b64 v[180:181], 5, v[176:177]
	s_lshl_b64 s[12:13], s[10:11], 5
	s_lshl_b64 s[14:15], s[10:11], 11
	s_mov_b64 s[16:17], 0
	s_movk_i32 s11, 0x41ff
	v_mov_b32_e32 v177, 0x358637bd
	s_mov_b32 s20, 0x800000
	s_mov_b32 s21, 0xf00000
	s_branch .LBB0_55

; __device__ __forceinline__ unsigned cvt_pk_bf16(float lo, float hi) { const f32v2_t v = {lo, hi}; const bf16v2_t r = __builtin_convertvector(v, bf16v2_t); return __builtin_bit_cast(unsigned, r); }
; __device__ __forceinline__ float bf2f(short b) { return __uint_as_float(((unsigned)(unsigned short)b) << 16); }
; __device__ __forceinline__ float silu_f(float x) { return x * __builtin_amdgcn_rcpf(1.0f + __expf(-x)); }
; __device__ __forceinline__ float sum16(float v) { v = sum8(v); v += dpp_f<0x140>(v); return v; }
; __device__ __forceinline__ void phase_onorm(const Params& p) {
;     ...
;     for (int idx = blockIdx.x * 512 + threadIdx.x; idx < total; idx += 4 * nthr) {
;         bf16x8 ov[4], gv[4];
; #pragma unroll
;         for (int q = 0; q < 4; ++q) { const int id = idx + q * nthr; const int row = (id < total ? id : idx) >> 6;
;             ov[q] = *(const bf16x8*)(CAT + (size_t)row * DM + 512 + c8); gv[q] = *(const bf16x8*)(Z + (size_t)row * NZ + ZC_BG + c8); }
; #pragma unroll
;         for (int q = 0; q < 4; ++q) {
;             const int id = idx + q * nthr;
;             float y[8]; float ss = 0.f;
; #pragma unroll
;             for (int e = 0; e < 8; ++e) { y[e] = bf2f(ov[q][e]); ss += y[e] * y[e]; }
;             ss = sum16(ss);
;             const float r = rsqrtf(ss * (1.0f / 128.0f) + 1e-6f);
; #pragma unroll
;             for (int e = 0; e < 8; ++e) y[e] = y[e] * r * nn[e] * silu_f(bf2f(gv[q][e]));
;             u32x4 w; w.x = cvt_pk_bf16(y[0], y[1]); w.y = cvt_pk_bf16(y[2], y[3]); w.z = cvt_pk_bf16(y[4], y[5]); w.w = cvt_pk_bf16(y[6], y[7]);
;             if (id < total) *(u32x4*)(CAT + (size_t)(id >> 6) * DM + 512 + c8) = w;
.LBB0_663:
	v_ashrrev_i32_e32 v8, 6, v12
	v_ashrrev_i32_e32 v9, 31, v8
	v_lshlrev_b64 v[10:11], 11, v[8:9]
	v_mad_i64_i32 v[8:9], s[2:3], v8, s16, v[32:33]
	v_lshl_add_u64 v[8:9], v[8:9], 0, v[28:29]
	v_add_co_u32_e32 v8, vcc, s17, v8
	v_lshl_add_u64 v[34:35], v[30:31], 0, v[10:11]
	s_nop 0
	v_addc_co_u32_e32 v9, vcc, 0, v9, vcc
	global_load_dwordx4 v[36:39], v[34:35], off offset:1024
	global_load_dwordx4 v[46:49], v[8:9], off offset:1536
	v_add_u32_e32 v44, s15, v12
	v_cmp_gt_i32_e32 vcc, s0, v44
	v_add_u32_e32 v43, s1, v12
	v_add_u32_e32 v45, s14, v12
	v_cndmask_b32_e32 v8, v12, v44, vcc
	v_ashrrev_i32_e32 v14, 6, v8
	v_mad_i64_i32 v[8:9], s[2:3], v14, s16, v[32:33]
	v_lshl_add_u64 v[8:9], v[8:9], 0, v[28:29]
	v_add_co_u32_e64 v8, s[2:3], s17, v8
	v_cmp_gt_i32_e64 s[4:5], s0, v43
	s_nop 0
	v_addc_co_u32_e64 v9, s[2:3], 0, v9, s[2:3]
	v_cndmask_b32_e64 v13, v12, v43, s[4:5]
	v_cmp_gt_i32_e64 s[2:3], s0, v45
	global_load_dwordx4 v[8:11], v[8:9], off offset:1536
	v_cndmask_b32_e64 v15, v12, v45, s[2:3]
	v_ashrrev_i32_e32 v12, 6, v13
	v_ashrrev_i32_e32 v16, 6, v15
	v_mad_i64_i32 v[18:19], s[6:7], v12, s16, v[32:33]
	v_mad_i64_i32 v[20:21], s[6:7], v16, s16, v[32:33]
	v_lshl_add_u64 v[18:19], v[18:19], 0, v[28:29]
	v_ashrrev_i32_e32 v13, 31, v12
	v_add_co_u32_e64 v54, s[6:7], s17, v18
	v_ashrrev_i32_e32 v17, 31, v16
	v_ashrrev_i32_e32 v15, 31, v14
	v_lshlrev_b64 v[12:13], 11, v[12:13]
	v_lshl_add_u64 v[20:21], v[20:21], 0, v[28:29]
	v_addc_co_u32_e64 v55, s[6:7], 0, v19, s[6:7]
	v_lshlrev_b64 v[16:17], 11, v[16:17]
	v_lshlrev_b64 v[14:15], 11, v[14:15]
	v_lshl_add_u64 v[40:41], v[30:31], 0, v[12:13]
	v_add_co_u32_e64 v58, s[6:7], s17, v20
	v_lshl_add_u64 v[56:57], v[30:31], 0, v[16:17]
	s_nop 0
	v_addc_co_u32_e64 v59, s[6:7], 0, v21, s[6:7]
	v_lshl_add_u64 v[60:61], v[30:31], 0, v[14:15]
	global_load_dwordx4 v[50:53], v[40:41], off offset:1024
	global_load_dwordx4 v[24:27], v[54:55], off offset:1536
	global_load_dwordx4 v[20:23], v[56:57], off offset:1024
	global_load_dwordx4 v[16:19], v[58:59], off offset:1536
	global_load_dwordx4 v[12:15], v[60:61], off offset:1024
	s_waitcnt vmcnt(5)
	v_lshlrev_b32_e32 v62, 16, v48
	v_and_b32_e32 v63, 0xffff0000, v48
	v_lshlrev_b32_e32 v64, 16, v47
	v_mul_f32_e32 v48, 0xbfb8aa3b, v62
	v_and_b32_e32 v65, 0xffff0000, v47
	v_mul_f32_e32 v66, 0xbfb8aa3b, v63
	v_mul_f32_e32 v67, 0xbfb8aa3b, v64
	v_exp_f32_e32 v48, v48
	v_mul_f32_e32 v68, 0xbfb8aa3b, v65
	v_exp_f32_e32 v66, v66
	v_exp_f32_e32 v67, v67
	v_exp_f32_e32 v68, v68
	v_and_b32_e32 v47, 0xffff0000, v46
	v_lshlrev_b32_e32 v46, 16, v46
	v_add_f32_e32 v48, 1.0, v48
	v_add_f32_e32 v69, 1.0, v66
	v_add_f32_e32 v70, 1.0, v67
	v_rcp_f32_e32 v66, v48
	v_mul_f32_e32 v48, 0xbfb8aa3b, v46
	v_add_f32_e32 v71, 1.0, v68
	v_rcp_f32_e32 v68, v70
	v_exp_f32_e32 v48, v48
	v_mul_f32_e32 v70, 0xbfb8aa3b, v47
	v_exp_f32_e32 v73, v70
	v_and_b32_e32 v55, 0xffff0000, v37
	v_lshlrev_b32_e32 v54, 16, v37
	v_and_b32_e32 v37, 0xffff0000, v36
	v_lshlrev_b32_e32 v36, 16, v36
	v_add_f32_e32 v48, 1.0, v48
	v_rcp_f32_e32 v67, v69
	v_rcp_f32_e32 v69, v71
	v_pk_mul_f32 v[70:71], v[36:37], v[36:37]
	v_rcp_f32_e32 v72, v48
	v_add_f32_e32 v48, 1.0, v73
	v_pk_mul_f32 v[60:61], v[54:55], v[54:55]
	v_rcp_f32_e32 v73, v48
	v_add_f32_e32 v48, v70, v71
	v_and_b32_e32 v41, 0xffff0000, v39
	v_lshlrev_b32_e32 v40, 16, v39
	v_and_b32_e32 v39, 0xffff0000, v38
	v_lshlrev_b32_e32 v38, 16, v38
	v_add_f32_e32 v48, v60, v48
	v_pk_mul_f32 v[58:59], v[38:39], v[38:39]
	v_add_f32_e32 v48, v61, v48
	v_add_f32_e32 v48, v58, v48
	v_pk_mul_f32 v[56:57], v[40:41], v[40:41]
	v_add_f32_e32 v48, v59, v48
	v_add_f32_e32 v48, v56, v48
	v_add_f32_e32 v48, v57, v48
	v_pk_mul_f32 v[46:47], v[72:73], v[46:47]
	v_pk_mul_f32 v[58:59], v[68:69], v[64:65]
	v_add_f32_dpp v48, v48, v48 quad_perm:[1,0,3,2] row_mask:0xf bank_mask:0xf bound_ctrl:1
	s_nop 1
	v_add_f32_dpp v48, v48, v48 quad_perm:[2,3,0,1] row_mask:0xf bank_mask:0xf bound_ctrl:1
	s_nop 1
	v_add_f32_dpp v48, v48, v48 row_half_mirror row_mask:0xf bank_mask:0xf bound_ctrl:1
	s_nop 1
	v_add_f32_dpp v48, v48, v48 row_mirror row_mask:0xf bank_mask:0xf bound_ctrl:1
	v_fmamk_f32 v48, v48, 0x3c000000, v42
	v_mul_f32_e32 v56, 0x4b800000, v48
	v_cmp_gt_f32_e64 s[6:7], s18, v48
	s_nop 1
	v_cndmask_b32_e64 v48, v48, v56, s[6:7]
	v_rsq_f32_e32 v48, v48
	v_pk_mul_f32 v[56:57], v[66:67], v[62:63]
	v_mul_f32_e32 v60, 0x45800000, v48
	v_cndmask_b32_e64 v48, v48, v60, s[6:7]
	v_pk_mul_f32 v[36:37], v[48:49], v[36:37] op_sel_hi:[0,1]
	v_pk_mul_f32 v[36:37], v[4:5], v[36:37]
	v_pk_mul_f32 v[38:39], v[48:49], v[38:39] op_sel_hi:[0,1]
	v_pk_mul_f32 v[36:37], v[46:47], v[36:37]
	v_pk_mul_f32 v[46:47], v[48:49], v[54:55] op_sel_hi:[0,1]
	v_lshlrev_b32_e32 v54, 16, v49
	v_pk_mul_f32 v[46:47], v[6:7], v[46:47]
	v_and_b32_e32 v55, 0xffff0000, v49
	v_mul_f32_e32 v49, 0xbfb8aa3b, v54
	v_pk_mul_f32 v[46:47], v[58:59], v[46:47]
	v_exp_f32_e32 v49, v49
	v_mul_f32_e32 v58, 0xbfb8aa3b, v55
	v_exp_f32_e32 v59, v58
	v_pk_mul_f32 v[38:39], v[0:1], v[38:39]
	v_add_f32_e32 v49, 1.0, v49
	v_rcp_f32_e32 v58, v49
	v_add_f32_e32 v49, 1.0, v59
	v_rcp_f32_e32 v59, v49
	v_pk_mul_f32 v[40:41], v[48:49], v[40:41] op_sel_hi:[0,1]
	v_pk_mul_f32 v[40:41], v[2:3], v[40:41]
	v_pk_mul_f32 v[38:39], v[56:57], v[38:39]
	v_pk_mul_f32 v[48:49], v[58:59], v[54:55]
	v_cvt_pk_bf16_f32 v36, v36, v37
	v_pk_mul_f32 v[40:41], v[48:49], v[40:41]
	v_cvt_pk_bf16_f32 v37, v46, v47
	v_cvt_pk_bf16_f32 v38, v38, v39
	v_cvt_pk_bf16_f32 v39, v40, v41
	s_waitcnt vmcnt(0)
	v_and_b32_e32 v41, 0xffff0000, v50
	v_lshlrev_b32_e32 v40, 16, v50
	global_store_dwordx4 v[34:35], v[36:39], off offset:1024
	v_pk_mul_f32 v[46:47], v[40:41], v[40:41]
	v_and_b32_e32 v35, 0xffff0000, v53
	v_and_b32_e32 v39, 0xffff0000, v51
	v_lshlrev_b32_e32 v38, 16, v51
	v_pk_mul_f32 v[48:49], v[38:39], v[38:39]
	v_add_f32_e32 v46, v46, v47
	v_and_b32_e32 v37, 0xffff0000, v52
	v_lshlrev_b32_e32 v36, 16, v52
	v_add_f32_e32 v46, v48, v46
	v_pk_mul_f32 v[50:51], v[36:37], v[36:37]
	v_add_f32_e32 v46, v49, v46
	v_lshlrev_b32_e32 v34, 16, v53
	v_add_f32_e32 v46, v50, v46
	v_pk_mul_f32 v[52:53], v[34:35], v[34:35]
	v_add_f32_e32 v46, v51, v46
	v_add_f32_e32 v46, v52, v46
	v_add_f32_e32 v46, v53, v46
	s_nop 1
	v_add_f32_dpp v46, v46, v46 quad_perm:[1,0,3,2] row_mask:0xf bank_mask:0xf bound_ctrl:1
	s_nop 1
	v_add_f32_dpp v46, v46, v46 quad_perm:[2,3,0,1] row_mask:0xf bank_mask:0xf bound_ctrl:1
	s_nop 1
	v_add_f32_dpp v46, v46, v46 row_half_mirror row_mask:0xf bank_mask:0xf bound_ctrl:1
	s_nop 1
	v_mov_b32_dpp v47, v46 row_mirror row_mask:0xf bank_mask:0xf bound_ctrl:1
	s_and_saveexec_b64 s[6:7], s[4:5]
	s_cbranch_execz .LBB0_665
; __device__ __forceinline__ unsigned cvt_pk_bf16(float lo, float hi) { const f32v2_t v = {lo, hi}; const bf16v2_t r = __builtin_convertvector(v, bf16v2_t); return __builtin_bit_cast(unsigned, r); }
; __device__ __forceinline__ float bf2f(short b) { return __uint_as_float(((unsigned)(unsigned short)b) << 16); }
; __device__ __forceinline__ float silu_f(float x) { return x * __builtin_amdgcn_rcpf(1.0f + __expf(-x)); }
; __device__ __forceinline__ float sum16(float v) { v = sum8(v); v += dpp_f<0x140>(v); return v; }
; __device__ __forceinline__ void phase_onorm(const Params& p) {
;     ...
;             for (int e = 0; e < 8; ++e) { y[e] = bf2f(ov[q][e]); ss += y[e] * y[e]; }
;             ss = sum16(ss);
;             const float r = rsqrtf(ss * (1.0f / 128.0f) + 1e-6f);
; #pragma unroll
;             for (int e = 0; e < 8; ++e) y[e] = y[e] * r * nn[e] * silu_f(bf2f(gv[q][e]));
;             u32x4 w; w.x = cvt_pk_bf16(y[0], y[1]); w.y = cvt_pk_bf16(y[2], y[3]); w.z = cvt_pk_bf16(y[4], y[5]); w.w = cvt_pk_bf16(y[6], y[7]);
;             if (id < total) *(u32x4*)(CAT + (size_t)(id >> 6) * DM + 512 + c8) = w;
	v_add_f32_e32 v46, v46, v47
	v_fmamk_f32 v46, v46, 0x3c000000, v42
	v_mul_f32_e32 v47, 0x4b800000, v46
	v_cmp_gt_f32_e64 s[4:5], s18, v46
	s_nop 1
	v_cndmask_b32_e64 v46, v46, v47, s[4:5]
	v_rsq_f32_e32 v47, v46
	v_lshlrev_b32_e32 v46, 16, v24
	v_mul_f32_e32 v48, 0xbfb8aa3b, v46
	v_exp_f32_e32 v49, v48
	v_mul_f32_e32 v48, 0x45800000, v47
	v_cndmask_b32_e64 v48, v47, v48, s[4:5]
	v_and_b32_e32 v47, 0xffff0000, v24
	v_add_f32_e32 v24, 1.0, v49
	v_mul_f32_e32 v49, 0xbfb8aa3b, v47
	v_exp_f32_e32 v49, v49
	v_rcp_f32_e32 v50, v24
	v_add_f32_e32 v24, 1.0, v49
	v_rcp_f32_e32 v51, v24
	v_pk_mul_f32 v[40:41], v[48:49], v[40:41] op_sel_hi:[0,1]
	v_pk_mul_f32 v[40:41], v[4:5], v[40:41]
	v_lshlrev_b32_e32 v24, 16, v25
	v_pk_mul_f32 v[46:47], v[50:51], v[46:47]
	v_and_b32_e32 v25, 0xffff0000, v25
	v_mul_f32_e32 v49, 0xbfb8aa3b, v24
	v_pk_mul_f32 v[40:41], v[46:47], v[40:41]
	v_mul_f32_e32 v47, 0xbfb8aa3b, v25
	v_exp_f32_e32 v49, v49
	v_exp_f32_e32 v47, v47
	v_lshlrev_b32_e32 v50, 16, v26
	v_and_b32_e32 v51, 0xffff0000, v26
	v_add_f32_e32 v46, 1.0, v49
	v_add_f32_e32 v47, 1.0, v47
	v_rcp_f32_e32 v46, v46
	v_rcp_f32_e32 v47, v47
	v_pk_mul_f32 v[38:39], v[48:49], v[38:39] op_sel_hi:[0,1]
	v_pk_mul_f32 v[38:39], v[6:7], v[38:39]
	v_mul_f32_e32 v49, 0xbfb8aa3b, v50
	v_pk_mul_f32 v[24:25], v[46:47], v[24:25]
	v_exp_f32_e32 v49, v49
	v_pk_mul_f32 v[38:39], v[24:25], v[38:39]
	v_mul_f32_e32 v25, 0xbfb8aa3b, v51
	v_exp_f32_e32 v25, v25
	v_and_b32_e32 v47, 0xffff0000, v27
	v_lshlrev_b32_e32 v46, 16, v27
	v_mul_f32_e32 v26, 0xbfb8aa3b, v46
	v_mul_f32_e32 v27, 0xbfb8aa3b, v47
	v_exp_f32_e32 v26, v26
	v_exp_f32_e32 v27, v27
	v_add_f32_e32 v24, 1.0, v49
	v_add_f32_e32 v25, 1.0, v25
	v_rcp_f32_e32 v24, v24
	v_rcp_f32_e32 v25, v25
	v_add_f32_e32 v26, 1.0, v26
	v_add_f32_e32 v27, 1.0, v27
	v_rcp_f32_e32 v26, v26
	v_rcp_f32_e32 v27, v27
	v_pk_mul_f32 v[36:37], v[48:49], v[36:37] op_sel_hi:[0,1]
	v_pk_mul_f32 v[36:37], v[0:1], v[36:37]
	v_pk_mul_f32 v[24:25], v[24:25], v[50:51]
	v_pk_mul_f32 v[26:27], v[26:27], v[46:47]
	v_pk_mul_f32 v[36:37], v[24:25], v[36:37]
	v_pk_mul_f32 v[24:25], v[48:49], v[34:35] op_sel_hi:[0,1]
	v_pk_mul_f32 v[24:25], v[2:3], v[24:25]
	s_nop 0
	v_pk_mul_f32 v[34:35], v[26:27], v[24:25]
	v_ashrrev_i32_e32 v24, 6, v43
	v_ashrrev_i32_e32 v25, 31, v24
	v_lshlrev_b64 v[24:25], 11, v[24:25]
	v_lshl_add_u64 v[46:47], v[30:31], 0, v[24:25]
	v_cvt_pk_bf16_f32 v24, v40, v41
	v_cvt_pk_bf16_f32 v25, v38, v39
	v_cvt_pk_bf16_f32 v26, v36, v37
	v_cvt_pk_bf16_f32 v27, v34, v35
	global_store_dwordx4 v[46:47], v[24:27], off offset:1024
